# SwiGLU epilogue output stores made write-through (sc1) so the hidden activations do not occupy L2 during the K-loops
# speedup vs baseline: 1.0219x; 1.0084x over previous
; __device__ __forceinline__ float silu_f(float x) { return x * __builtin_amdgcn_rcpf(1.0f + __builtin_amdgcn_exp2f(-1.4426950408889634f * x)); }
;     __device__ __forceinline__ void operator()(const i32x4 (&acc)[2][2][4][2], const pg8::Unit& u, int wr, int wc, int fr_, int fq_, int tid) {
;         int fr = fr_, fq = fq_; asm volatile("" : "+v"(fr), "+v"(fq));
;         if (skip) return;
;         const int row0 = u.pm * 256 + wr * 64 + fr, col0 = u.pn * 128 + wc * 32 + 8 * fq;
;         const float* cp = cmax + u.pn * 256 + wc * 32 + 8 * fq;
;         f32x4 cs[2][2];
;         cs[0][0] = *(const f32x4*)(cp) * (1.0f / 127.0f); cs[0][1] = *(const f32x4*)(cp + 4) * (1.0f / 127.0f);
;         cs[1][0] = *(const f32x4*)(cp + 128) * (1.0f / 127.0f); cs[1][1] = *(const f32x4*)(cp + 132) * (1.0f / 127.0f);
; #pragma unroll
;         for (int ai = 0; ai < 2; ++ai)
; #pragma unroll
;             for (int m = 0; m < 4; ++m) {
;                 const int row = row0 + ai * 128 + m * 16;
;                 const float rs = rsl[wr * 64 + fr + ai * 128 + m * 16];
;                 f32x4 h[2];
; #pragma unroll
;                 for (int n = 0; n < 2; ++n) {
; #pragma unroll
;                     for (int i = 0; i < 4; ++i) { const float g = (float)acc[ai][0][m][n][i] * (rs * cs[0][n][i]), up = (float)acc[ai][1][m][n][i] * (rs * cs[1][n][i]); h[n][i] = silu_f(g) * up; } }
;                 *(u32x4*)(H + ((size_t)(u.pm * (DFF / 64) + (col0 >> 6)) * 256 + (size_t)(row & 255)) * 64 + (col0 & 63)) = pack8bf(h[0], h[1]);
;             }
;     }
.LBB0_166:
	s_mul_i32 s13, s20, 0x58
	v_lshrrev_b32_e32 v175, 4, v195
	s_lshl_b32 s22, s21, 10
	v_and_b32_e32 v174, 15, v195
	s_add_u32 s22, s45, s22
	s_addc_u32 s23, s46, 0
	v_lshlrev_b32_e32 v176, 4, v175
	v_lshlrev_b32_e32 v175, 5, v175
	global_load_dwordx4 v[216:219], v175, s[22:23]
	global_load_dwordx4 v[220:223], v175, s[22:23] offset:16
	global_load_dwordx4 v[224:227], v175, s[22:23] offset:512
	global_load_dwordx4 v[228:231], v175, s[22:23] offset:528
	v_add_u32_e32 v177, s40, v174
	v_lshl_add_u32 v174, v174, 2, s47
	ds_read_b32 v232, v174
	ds_read_b32 v234, v174 offset:64
	ds_read_b32 v236, v174 offset:128
	ds_read_b32 v238, v174 offset:192
	ds_read_b32 v240, v174 offset:512
	ds_read_b32 v242, v174 offset:576
	ds_read_b32 v244, v174 offset:640
	ds_read_b32 v246, v174 offset:704
	v_lshl_add_u32 v176, v177, 7, v176
	s_lshl_b32 s22, s21, 1
	s_add_i32 s13, s13, s22
	s_lshr_b32 s22, s41, 6
	s_add_i32 s13, s13, s22
	s_and_b32 s22, s41, 32
	s_lshl_b32 s22, s22, 1
	v_add_u32_e32 v176, s22, v176
	s_lshl_b32 s13, s13, 15
	s_add_u32 s20, s8, s13
	s_addc_u32 s21, s9, 0
	v_cvt_f32_i32_e32 v126, v126
	v_cvt_f32_i32_e32 v127, v127
	v_cvt_f32_i32_e32 v128, v128
	v_cvt_f32_i32_e32 v129, v129
	v_cvt_f32_i32_e32 v122, v122
	v_cvt_f32_i32_e32 v123, v123
	v_cvt_f32_i32_e32 v124, v124
	v_cvt_f32_i32_e32 v125, v125
	v_cvt_f32_i32_e32 v118, v118
	v_cvt_f32_i32_e32 v119, v119
	v_cvt_f32_i32_e32 v120, v120
	v_cvt_f32_i32_e32 v121, v121
	v_cvt_f32_i32_e32 v114, v114
	v_cvt_f32_i32_e32 v115, v115
	v_cvt_f32_i32_e32 v116, v116
	v_cvt_f32_i32_e32 v117, v117
	v_cvt_f32_i32_e32 v110, v110
	v_cvt_f32_i32_e32 v111, v111
	v_cvt_f32_i32_e32 v112, v112
	v_cvt_f32_i32_e32 v113, v113
	v_cvt_f32_i32_e32 v106, v106
	v_cvt_f32_i32_e32 v107, v107
	v_cvt_f32_i32_e32 v108, v108
	v_cvt_f32_i32_e32 v109, v109
	v_cvt_f32_i32_e32 v102, v102
	v_cvt_f32_i32_e32 v103, v103
	v_cvt_f32_i32_e32 v104, v104
	v_cvt_f32_i32_e32 v105, v105
	v_cvt_f32_i32_e32 v98, v98
	v_cvt_f32_i32_e32 v99, v99
	v_cvt_f32_i32_e32 v100, v100
	v_cvt_f32_i32_e32 v101, v101
	s_waitcnt vmcnt(0) lgkmcnt(0)
	v_pk_mul_f32 v[216:217], v[216:217], s[76:77] op_sel_hi:[1,0]
	v_pk_mul_f32 v[218:219], v[218:219], s[76:77] op_sel_hi:[1,0]
	v_pk_mul_f32 v[220:221], v[220:221], s[76:77] op_sel_hi:[1,0]
	v_pk_mul_f32 v[222:223], v[222:223], s[76:77] op_sel_hi:[1,0]
	v_pk_mul_f32 v[224:225], v[224:225], s[76:77] op_sel_hi:[1,0]
	v_pk_mul_f32 v[226:227], v[226:227], s[76:77] op_sel_hi:[1,0]
	v_pk_mul_f32 v[228:229], v[228:229], s[76:77] op_sel_hi:[1,0]
	v_pk_mul_f32 v[230:231], v[230:231], s[76:77] op_sel_hi:[1,0]
	v_mul_f32_e32 v233, v232, v232
	v_mul_f32_e32 v235, v234, v234
	v_mul_f32_e32 v237, v236, v236
	v_mul_f32_e32 v239, v238, v238
	v_mul_f32_e32 v241, v240, v240
	v_mul_f32_e32 v243, v242, v242
	v_mul_f32_e32 v245, v244, v244
	v_mul_f32_e32 v247, v246, v246
	v_mul_f32_e32 v232, 0xbfb8aa3b, v232
	v_mul_f32_e32 v234, 0xbfb8aa3b, v234
	v_mul_f32_e32 v236, 0xbfb8aa3b, v236
	v_mul_f32_e32 v238, 0xbfb8aa3b, v238
	v_mul_f32_e32 v240, 0xbfb8aa3b, v240
	v_mul_f32_e32 v242, 0xbfb8aa3b, v242
	v_mul_f32_e32 v244, 0xbfb8aa3b, v244
	v_mul_f32_e32 v246, 0xbfb8aa3b, v246
	v_cvt_f32_i32_e32 v94, v94
	v_cvt_f32_i32_e32 v95, v95
	v_cvt_f32_i32_e32 v96, v96
	v_cvt_f32_i32_e32 v97, v97
	v_cvt_f32_i32_e32 v90, v90
	v_cvt_f32_i32_e32 v91, v91
	v_cvt_f32_i32_e32 v92, v92
	v_cvt_f32_i32_e32 v93, v93
	v_cvt_f32_i32_e32 v86, v86
	v_cvt_f32_i32_e32 v87, v87
	v_cvt_f32_i32_e32 v88, v88
	v_cvt_f32_i32_e32 v89, v89
	v_cvt_f32_i32_e32 v82, v82
	v_cvt_f32_i32_e32 v83, v83
	v_cvt_f32_i32_e32 v84, v84
	v_cvt_f32_i32_e32 v85, v85
	v_pk_mul_f32 v[126:127], v[126:127], v[216:217]
	v_pk_mul_f32 v[128:129], v[128:129], v[218:219]
	v_pk_mul_f32 v[122:123], v[122:123], v[224:225]
	v_pk_mul_f32 v[124:125], v[124:125], v[226:227]
	v_pk_mul_f32 v[248:249], v[126:127], v[232:233] op_sel_hi:[1,0]
	v_pk_mul_f32 v[250:251], v[128:129], v[232:233] op_sel_hi:[1,0]
	v_pk_mul_f32 v[126:127], v[126:127], v[122:123]
	v_exp_f32_e32 v248, v248
	v_exp_f32_e32 v249, v249
	v_exp_f32_e32 v250, v250
	v_exp_f32_e32 v251, v251
	v_pk_mul_f32 v[128:129], v[128:129], v[124:125]
	v_pk_add_f32 v[248:249], v[248:249], 1.0 op_sel_hi:[1,0]
	v_pk_add_f32 v[250:251], v[250:251], 1.0 op_sel_hi:[1,0]
	v_rcp_f32_e32 v248, v248
	v_rcp_f32_e32 v249, v249
	v_rcp_f32_e32 v250, v250
	v_rcp_f32_e32 v251, v251
	v_pk_mul_f32 v[248:249], v[248:249], v[232:233] op_sel:[0,1] op_sel_hi:[1,1]
	v_pk_mul_f32 v[250:251], v[250:251], v[232:233] op_sel:[0,1] op_sel_hi:[1,1]
	v_pk_mul_f32 v[126:127], v[126:127], v[248:249]
	v_pk_mul_f32 v[128:129], v[128:129], v[250:251]
	v_cvt_pk_bf16_f32 v122, v126, v127
	v_cvt_pk_bf16_f32 v123, v128, v129
	v_pk_mul_f32 v[118:119], v[118:119], v[220:221]
	v_pk_mul_f32 v[120:121], v[120:121], v[222:223]
	v_pk_mul_f32 v[114:115], v[114:115], v[228:229]
	v_pk_mul_f32 v[116:117], v[116:117], v[230:231]
	v_pk_mul_f32 v[248:249], v[118:119], v[232:233] op_sel_hi:[1,0]
	v_pk_mul_f32 v[250:251], v[120:121], v[232:233] op_sel_hi:[1,0]
	v_pk_mul_f32 v[118:119], v[118:119], v[114:115]
	v_exp_f32_e32 v248, v248
	v_exp_f32_e32 v249, v249
	v_exp_f32_e32 v250, v250
	v_exp_f32_e32 v251, v251
	v_pk_mul_f32 v[120:121], v[120:121], v[116:117]
	v_pk_add_f32 v[248:249], v[248:249], 1.0 op_sel_hi:[1,0]
	v_pk_add_f32 v[250:251], v[250:251], 1.0 op_sel_hi:[1,0]
	v_rcp_f32_e32 v248, v248
	v_rcp_f32_e32 v249, v249
	v_rcp_f32_e32 v250, v250
	v_rcp_f32_e32 v251, v251
	v_pk_mul_f32 v[248:249], v[248:249], v[232:233] op_sel:[0,1] op_sel_hi:[1,1]
	v_pk_mul_f32 v[250:251], v[250:251], v[232:233] op_sel:[0,1] op_sel_hi:[1,1]
	v_pk_mul_f32 v[118:119], v[118:119], v[248:249]
	v_pk_mul_f32 v[120:121], v[120:121], v[250:251]
; __device__ __forceinline__ float silu_f(float x) { return x * __builtin_amdgcn_rcpf(1.0f + __builtin_amdgcn_exp2f(-1.4426950408889634f * x)); }
;     __device__ __forceinline__ void operator()(const i32x4 (&acc)[2][2][4][2], const pg8::Unit& u, int wr, int wc, int fr_, int fq_, int tid) {
;     ...
;             for (int m = 0; m < 4; ++m) {
;                 const int row = row0 + ai * 128 + m * 16;
;                 const float rs = rsl[wr * 64 + fr + ai * 128 + m * 16];
;                 f32x4 h[2];
; #pragma unroll
;                 for (int n = 0; n < 2; ++n) {
; #pragma unroll
;                     for (int i = 0; i < 4; ++i) { const float g = (float)acc[ai][0][m][n][i] * (rs * cs[0][n][i]), up = (float)acc[ai][1][m][n][i] * (rs * cs[1][n][i]); h[n][i] = silu_f(g) * up; } }
;                 *(u32x4*)(H + ((size_t)(u.pm * (DFF / 64) + (col0 >> 6)) * 256 + (size_t)(row & 255)) * 64 + (col0 & 63)) = pack8bf(h[0], h[1]);
;             }
;     }
	v_cvt_pk_bf16_f32 v124, v118, v119
	v_cvt_pk_bf16_f32 v125, v120, v121
	s_mov_b64 s[22:23], s[20:21]
	global_store_dwordx4 v176, v[122:125], s[22:23] sc1
	v_cvt_f32_i32_e32 v78, v78
	v_cvt_f32_i32_e32 v79, v79
	v_cvt_f32_i32_e32 v80, v80
	v_cvt_f32_i32_e32 v81, v81
	v_cvt_f32_i32_e32 v74, v74
	v_cvt_f32_i32_e32 v75, v75
	v_cvt_f32_i32_e32 v76, v76
	v_cvt_f32_i32_e32 v77, v77
	v_cvt_f32_i32_e32 v70, v70
	v_cvt_f32_i32_e32 v71, v71
	v_cvt_f32_i32_e32 v72, v72
	v_cvt_f32_i32_e32 v73, v73
	v_cvt_f32_i32_e32 v66, v66
	v_cvt_f32_i32_e32 v67, v67
	v_cvt_f32_i32_e32 v68, v68
	v_cvt_f32_i32_e32 v69, v69
	v_pk_mul_f32 v[110:111], v[110:111], v[216:217]
	v_pk_mul_f32 v[112:113], v[112:113], v[218:219]
	v_pk_mul_f32 v[106:107], v[106:107], v[224:225]
	v_pk_mul_f32 v[108:109], v[108:109], v[226:227]
	v_pk_mul_f32 v[248:249], v[110:111], v[234:235] op_sel_hi:[1,0]
	v_pk_mul_f32 v[250:251], v[112:113], v[234:235] op_sel_hi:[1,0]
	v_pk_mul_f32 v[110:111], v[110:111], v[106:107]
	v_exp_f32_e32 v248, v248
	v_exp_f32_e32 v249, v249
	v_exp_f32_e32 v250, v250
	v_exp_f32_e32 v251, v251
	v_pk_mul_f32 v[112:113], v[112:113], v[108:109]
	v_pk_add_f32 v[248:249], v[248:249], 1.0 op_sel_hi:[1,0]
	v_pk_add_f32 v[250:251], v[250:251], 1.0 op_sel_hi:[1,0]
	v_rcp_f32_e32 v248, v248
	v_rcp_f32_e32 v249, v249
	v_rcp_f32_e32 v250, v250
	v_rcp_f32_e32 v251, v251
	v_pk_mul_f32 v[248:249], v[248:249], v[234:235] op_sel:[0,1] op_sel_hi:[1,1]
	v_pk_mul_f32 v[250:251], v[250:251], v[234:235] op_sel:[0,1] op_sel_hi:[1,1]
	v_pk_mul_f32 v[110:111], v[110:111], v[248:249]
	v_pk_mul_f32 v[112:113], v[112:113], v[250:251]
	v_cvt_pk_bf16_f32 v106, v110, v111
	v_cvt_pk_bf16_f32 v107, v112, v113
	v_pk_mul_f32 v[102:103], v[102:103], v[220:221]
	v_pk_mul_f32 v[104:105], v[104:105], v[222:223]
	v_pk_mul_f32 v[98:99], v[98:99], v[228:229]
	v_pk_mul_f32 v[100:101], v[100:101], v[230:231]
	v_pk_mul_f32 v[248:249], v[102:103], v[234:235] op_sel_hi:[1,0]
	v_pk_mul_f32 v[250:251], v[104:105], v[234:235] op_sel_hi:[1,0]
	v_pk_mul_f32 v[102:103], v[102:103], v[98:99]
	v_exp_f32_e32 v248, v248
	v_exp_f32_e32 v249, v249
	v_exp_f32_e32 v250, v250
	v_exp_f32_e32 v251, v251
	v_pk_mul_f32 v[104:105], v[104:105], v[100:101]
	v_pk_add_f32 v[248:249], v[248:249], 1.0 op_sel_hi:[1,0]
	v_pk_add_f32 v[250:251], v[250:251], 1.0 op_sel_hi:[1,0]
	v_rcp_f32_e32 v248, v248
	v_rcp_f32_e32 v249, v249
	v_rcp_f32_e32 v250, v250
	v_rcp_f32_e32 v251, v251
	v_pk_mul_f32 v[248:249], v[248:249], v[234:235] op_sel:[0,1] op_sel_hi:[1,1]
	v_pk_mul_f32 v[250:251], v[250:251], v[234:235] op_sel:[0,1] op_sel_hi:[1,1]
	v_pk_mul_f32 v[102:103], v[102:103], v[248:249]
	v_pk_mul_f32 v[104:105], v[104:105], v[250:251]
	v_cvt_pk_bf16_f32 v108, v102, v103
	v_cvt_pk_bf16_f32 v109, v104, v105
	global_store_dwordx4 v176, v[106:109], s[22:23] offset:2048 sc1
	v_cvt_f32_i32_e32 v62, v62
	v_cvt_f32_i32_e32 v63, v63
	v_cvt_f32_i32_e32 v64, v64
	v_cvt_f32_i32_e32 v65, v65
	v_cvt_f32_i32_e32 v58, v58
	v_cvt_f32_i32_e32 v59, v59
	v_cvt_f32_i32_e32 v60, v60
	v_cvt_f32_i32_e32 v61, v61
	v_cvt_f32_i32_e32 v54, v54
	v_cvt_f32_i32_e32 v55, v55
	v_cvt_f32_i32_e32 v56, v56
	v_cvt_f32_i32_e32 v57, v57
	v_cvt_f32_i32_e32 v50, v50
	v_cvt_f32_i32_e32 v51, v51
	v_cvt_f32_i32_e32 v52, v52
	v_cvt_f32_i32_e32 v53, v53
	v_pk_mul_f32 v[94:95], v[94:95], v[216:217]
	v_pk_mul_f32 v[96:97], v[96:97], v[218:219]
	v_pk_mul_f32 v[90:91], v[90:91], v[224:225]
	v_pk_mul_f32 v[92:93], v[92:93], v[226:227]
	v_pk_mul_f32 v[248:249], v[94:95], v[236:237] op_sel_hi:[1,0]
	v_pk_mul_f32 v[250:251], v[96:97], v[236:237] op_sel_hi:[1,0]
	v_pk_mul_f32 v[94:95], v[94:95], v[90:91]
	v_exp_f32_e32 v248, v248
	v_exp_f32_e32 v249, v249
	v_exp_f32_e32 v250, v250
	v_exp_f32_e32 v251, v251
	v_pk_mul_f32 v[96:97], v[96:97], v[92:93]
	v_pk_add_f32 v[248:249], v[248:249], 1.0 op_sel_hi:[1,0]
	v_pk_add_f32 v[250:251], v[250:251], 1.0 op_sel_hi:[1,0]
	v_rcp_f32_e32 v248, v248
	v_rcp_f32_e32 v249, v249
	v_rcp_f32_e32 v250, v250
	v_rcp_f32_e32 v251, v251
	v_pk_mul_f32 v[248:249], v[248:249], v[236:237] op_sel:[0,1] op_sel_hi:[1,1]
	v_pk_mul_f32 v[250:251], v[250:251], v[236:237] op_sel:[0,1] op_sel_hi:[1,1]
	v_pk_mul_f32 v[94:95], v[94:95], v[248:249]
	v_pk_mul_f32 v[96:97], v[96:97], v[250:251]
	v_cvt_pk_bf16_f32 v90, v94, v95
	v_cvt_pk_bf16_f32 v91, v96, v97
	v_pk_mul_f32 v[86:87], v[86:87], v[220:221]
	v_pk_mul_f32 v[88:89], v[88:89], v[222:223]
	v_pk_mul_f32 v[82:83], v[82:83], v[228:229]
	v_pk_mul_f32 v[84:85], v[84:85], v[230:231]
	v_pk_mul_f32 v[248:249], v[86:87], v[236:237] op_sel_hi:[1,0]
	v_pk_mul_f32 v[250:251], v[88:89], v[236:237] op_sel_hi:[1,0]
	v_pk_mul_f32 v[86:87], v[86:87], v[82:83]
	v_exp_f32_e32 v248, v248
	v_exp_f32_e32 v249, v249
	v_exp_f32_e32 v250, v250
	v_exp_f32_e32 v251, v251
	v_pk_mul_f32 v[88:89], v[88:89], v[84:85]
	v_pk_add_f32 v[248:249], v[248:249], 1.0 op_sel_hi:[1,0]
	v_pk_add_f32 v[250:251], v[250:251], 1.0 op_sel_hi:[1,0]
	v_rcp_f32_e32 v248, v248
	v_rcp_f32_e32 v249, v249
	v_rcp_f32_e32 v250, v250
	v_rcp_f32_e32 v251, v251
	v_pk_mul_f32 v[248:249], v[248:249], v[236:237] op_sel:[0,1] op_sel_hi:[1,1]
	v_pk_mul_f32 v[250:251], v[250:251], v[236:237] op_sel:[0,1] op_sel_hi:[1,1]
	v_pk_mul_f32 v[86:87], v[86:87], v[248:249]
	v_pk_mul_f32 v[88:89], v[88:89], v[250:251]
	v_cvt_pk_bf16_f32 v92, v86, v87
	v_cvt_pk_bf16_f32 v93, v88, v89
	s_add_u32 s22, s20, 0x1000
	s_addc_u32 s23, s21, 0
	global_store_dwordx4 v176, v[90:93], s[22:23] sc1
	v_cvt_f32_i32_e32 v46, v46
	v_cvt_f32_i32_e32 v47, v47
	v_cvt_f32_i32_e32 v48, v48
	v_cvt_f32_i32_e32 v49, v49
	v_cvt_f32_i32_e32 v42, v42
	v_cvt_f32_i32_e32 v43, v43
	v_cvt_f32_i32_e32 v44, v44
	v_cvt_f32_i32_e32 v45, v45
; __device__ __forceinline__ float silu_f(float x) { return x * __builtin_amdgcn_rcpf(1.0f + __builtin_amdgcn_exp2f(-1.4426950408889634f * x)); }
;     __device__ __forceinline__ void operator()(const i32x4 (&acc)[2][2][4][2], const pg8::Unit& u, int wr, int wc, int fr_, int fq_, int tid) {
;     ...
;             for (int m = 0; m < 4; ++m) {
;                 const int row = row0 + ai * 128 + m * 16;
;                 const float rs = rsl[wr * 64 + fr + ai * 128 + m * 16];
;                 f32x4 h[2];
; #pragma unroll
;                 for (int n = 0; n < 2; ++n) {
; #pragma unroll
;                     for (int i = 0; i < 4; ++i) { const float g = (float)acc[ai][0][m][n][i] * (rs * cs[0][n][i]), up = (float)acc[ai][1][m][n][i] * (rs * cs[1][n][i]); h[n][i] = silu_f(g) * up; } }
;                 *(u32x4*)(H + ((size_t)(u.pm * (DFF / 64) + (col0 >> 6)) * 256 + (size_t)(row & 255)) * 64 + (col0 & 63)) = pack8bf(h[0], h[1]);
;             }
;     }
	v_cvt_f32_i32_e32 v38, v38
	v_cvt_f32_i32_e32 v39, v39
	v_cvt_f32_i32_e32 v40, v40
	v_cvt_f32_i32_e32 v41, v41
	v_cvt_f32_i32_e32 v34, v34
	v_cvt_f32_i32_e32 v35, v35
	v_cvt_f32_i32_e32 v36, v36
	v_cvt_f32_i32_e32 v37, v37
	v_pk_mul_f32 v[78:79], v[78:79], v[216:217]
	v_pk_mul_f32 v[80:81], v[80:81], v[218:219]
	v_pk_mul_f32 v[74:75], v[74:75], v[224:225]
	v_pk_mul_f32 v[76:77], v[76:77], v[226:227]
	v_pk_mul_f32 v[248:249], v[78:79], v[238:239] op_sel_hi:[1,0]
	v_pk_mul_f32 v[250:251], v[80:81], v[238:239] op_sel_hi:[1,0]
	v_pk_mul_f32 v[78:79], v[78:79], v[74:75]
	v_exp_f32_e32 v248, v248
	v_exp_f32_e32 v249, v249
	v_exp_f32_e32 v250, v250
	v_exp_f32_e32 v251, v251
	v_pk_mul_f32 v[80:81], v[80:81], v[76:77]
	v_pk_add_f32 v[248:249], v[248:249], 1.0 op_sel_hi:[1,0]
	v_pk_add_f32 v[250:251], v[250:251], 1.0 op_sel_hi:[1,0]
	v_rcp_f32_e32 v248, v248
	v_rcp_f32_e32 v249, v249
	v_rcp_f32_e32 v250, v250
	v_rcp_f32_e32 v251, v251
	v_pk_mul_f32 v[248:249], v[248:249], v[238:239] op_sel:[0,1] op_sel_hi:[1,1]
	v_pk_mul_f32 v[250:251], v[250:251], v[238:239] op_sel:[0,1] op_sel_hi:[1,1]
	v_pk_mul_f32 v[78:79], v[78:79], v[248:249]
	v_pk_mul_f32 v[80:81], v[80:81], v[250:251]
	v_cvt_pk_bf16_f32 v74, v78, v79
	v_cvt_pk_bf16_f32 v75, v80, v81
	v_pk_mul_f32 v[70:71], v[70:71], v[220:221]
	v_pk_mul_f32 v[72:73], v[72:73], v[222:223]
	v_pk_mul_f32 v[66:67], v[66:67], v[228:229]
	v_pk_mul_f32 v[68:69], v[68:69], v[230:231]
	v_pk_mul_f32 v[248:249], v[70:71], v[238:239] op_sel_hi:[1,0]
	v_pk_mul_f32 v[250:251], v[72:73], v[238:239] op_sel_hi:[1,0]
	v_pk_mul_f32 v[70:71], v[70:71], v[66:67]
	v_exp_f32_e32 v248, v248
	v_exp_f32_e32 v249, v249
	v_exp_f32_e32 v250, v250
	v_exp_f32_e32 v251, v251
	v_pk_mul_f32 v[72:73], v[72:73], v[68:69]
	v_pk_add_f32 v[248:249], v[248:249], 1.0 op_sel_hi:[1,0]
	v_pk_add_f32 v[250:251], v[250:251], 1.0 op_sel_hi:[1,0]
	v_rcp_f32_e32 v248, v248
	v_rcp_f32_e32 v249, v249
	v_rcp_f32_e32 v250, v250
	v_rcp_f32_e32 v251, v251
	v_pk_mul_f32 v[248:249], v[248:249], v[238:239] op_sel:[0,1] op_sel_hi:[1,1]
	v_pk_mul_f32 v[250:251], v[250:251], v[238:239] op_sel:[0,1] op_sel_hi:[1,1]
	v_pk_mul_f32 v[70:71], v[70:71], v[248:249]
	v_pk_mul_f32 v[72:73], v[72:73], v[250:251]
	v_cvt_pk_bf16_f32 v76, v70, v71
	v_cvt_pk_bf16_f32 v77, v72, v73
	global_store_dwordx4 v176, v[74:77], s[22:23] offset:2048 sc1
	v_cvt_f32_i32_e32 v30, v30
	v_cvt_f32_i32_e32 v31, v31
	v_cvt_f32_i32_e32 v32, v32
	v_cvt_f32_i32_e32 v33, v33
	v_cvt_f32_i32_e32 v26, v26
	v_cvt_f32_i32_e32 v27, v27
	v_cvt_f32_i32_e32 v28, v28
	v_cvt_f32_i32_e32 v29, v29
	v_cvt_f32_i32_e32 v22, v22
	v_cvt_f32_i32_e32 v23, v23
	v_cvt_f32_i32_e32 v24, v24
	v_cvt_f32_i32_e32 v25, v25
	v_cvt_f32_i32_e32 v18, v18
	v_cvt_f32_i32_e32 v19, v19
	v_cvt_f32_i32_e32 v20, v20
	v_cvt_f32_i32_e32 v21, v21
	v_pk_mul_f32 v[62:63], v[62:63], v[216:217]
	v_pk_mul_f32 v[64:65], v[64:65], v[218:219]
	v_pk_mul_f32 v[58:59], v[58:59], v[224:225]
	v_pk_mul_f32 v[60:61], v[60:61], v[226:227]
	v_pk_mul_f32 v[248:249], v[62:63], v[240:241] op_sel_hi:[1,0]
	v_pk_mul_f32 v[250:251], v[64:65], v[240:241] op_sel_hi:[1,0]
	v_pk_mul_f32 v[62:63], v[62:63], v[58:59]
	v_exp_f32_e32 v248, v248
	v_exp_f32_e32 v249, v249
	v_exp_f32_e32 v250, v250
	v_exp_f32_e32 v251, v251
	v_pk_mul_f32 v[64:65], v[64:65], v[60:61]
	v_pk_add_f32 v[248:249], v[248:249], 1.0 op_sel_hi:[1,0]
	v_pk_add_f32 v[250:251], v[250:251], 1.0 op_sel_hi:[1,0]
	v_rcp_f32_e32 v248, v248
	v_rcp_f32_e32 v249, v249
	v_rcp_f32_e32 v250, v250
	v_rcp_f32_e32 v251, v251
	v_pk_mul_f32 v[248:249], v[248:249], v[240:241] op_sel:[0,1] op_sel_hi:[1,1]
	v_pk_mul_f32 v[250:251], v[250:251], v[240:241] op_sel:[0,1] op_sel_hi:[1,1]
	v_pk_mul_f32 v[62:63], v[62:63], v[248:249]
	v_pk_mul_f32 v[64:65], v[64:65], v[250:251]
	v_cvt_pk_bf16_f32 v58, v62, v63
	v_cvt_pk_bf16_f32 v59, v64, v65
	v_pk_mul_f32 v[54:55], v[54:55], v[220:221]
	v_pk_mul_f32 v[56:57], v[56:57], v[222:223]
	v_pk_mul_f32 v[50:51], v[50:51], v[228:229]
	v_pk_mul_f32 v[52:53], v[52:53], v[230:231]
	v_pk_mul_f32 v[248:249], v[54:55], v[240:241] op_sel_hi:[1,0]
	v_pk_mul_f32 v[250:251], v[56:57], v[240:241] op_sel_hi:[1,0]
	v_pk_mul_f32 v[54:55], v[54:55], v[50:51]
	v_exp_f32_e32 v248, v248
	v_exp_f32_e32 v249, v249
	v_exp_f32_e32 v250, v250
	v_exp_f32_e32 v251, v251
	v_pk_mul_f32 v[56:57], v[56:57], v[52:53]
	v_pk_add_f32 v[248:249], v[248:249], 1.0 op_sel_hi:[1,0]
	v_pk_add_f32 v[250:251], v[250:251], 1.0 op_sel_hi:[1,0]
	v_rcp_f32_e32 v248, v248
	v_rcp_f32_e32 v249, v249
	v_rcp_f32_e32 v250, v250
	v_rcp_f32_e32 v251, v251
	v_pk_mul_f32 v[248:249], v[248:249], v[240:241] op_sel:[0,1] op_sel_hi:[1,1]
	v_pk_mul_f32 v[250:251], v[250:251], v[240:241] op_sel:[0,1] op_sel_hi:[1,1]
	v_pk_mul_f32 v[54:55], v[54:55], v[248:249]
	v_pk_mul_f32 v[56:57], v[56:57], v[250:251]
	v_cvt_pk_bf16_f32 v60, v54, v55
	v_cvt_pk_bf16_f32 v61, v56, v57
	s_add_u32 s22, s20, 0x4000
	s_addc_u32 s23, s21, 0
	global_store_dwordx4 v176, v[58:61], s[22:23] sc1
	v_cvt_f32_i32_e32 v14, v14
	v_cvt_f32_i32_e32 v15, v15
	v_cvt_f32_i32_e32 v16, v16
	v_cvt_f32_i32_e32 v17, v17
	v_cvt_f32_i32_e32 v10, v10
	v_cvt_f32_i32_e32 v11, v11
	v_cvt_f32_i32_e32 v12, v12
	v_cvt_f32_i32_e32 v13, v13
	v_cvt_f32_i32_e32 v6, v6
	v_cvt_f32_i32_e32 v7, v7
	v_cvt_f32_i32_e32 v8, v8
	v_cvt_f32_i32_e32 v9, v9
	v_cvt_f32_i32_e32 v2, v2
	v_cvt_f32_i32_e32 v3, v3
	v_cvt_f32_i32_e32 v4, v4
	v_cvt_f32_i32_e32 v5, v5
	v_pk_mul_f32 v[46:47], v[46:47], v[216:217]
	v_pk_mul_f32 v[48:49], v[48:49], v[218:219]
	v_pk_mul_f32 v[42:43], v[42:43], v[224:225]
	v_pk_mul_f32 v[44:45], v[44:45], v[226:227]
	v_pk_mul_f32 v[248:249], v[46:47], v[242:243] op_sel_hi:[1,0]
; __device__ __forceinline__ float silu_f(float x) { return x * __builtin_amdgcn_rcpf(1.0f + __builtin_amdgcn_exp2f(-1.4426950408889634f * x)); }
;     __device__ __forceinline__ void operator()(const i32x4 (&acc)[2][2][4][2], const pg8::Unit& u, int wr, int wc, int fr_, int fq_, int tid) {
;     ...
;         for (int ai = 0; ai < 2; ++ai)
; #pragma unroll
;             for (int m = 0; m < 4; ++m) {
;                 const int row = row0 + ai * 128 + m * 16;
;                 const float rs = rsl[wr * 64 + fr + ai * 128 + m * 16];
;                 f32x4 h[2];
; #pragma unroll
;                 for (int n = 0; n < 2; ++n) {
; #pragma unroll
;                     for (int i = 0; i < 4; ++i) { const float g = (float)acc[ai][0][m][n][i] * (rs * cs[0][n][i]), up = (float)acc[ai][1][m][n][i] * (rs * cs[1][n][i]); h[n][i] = silu_f(g) * up; } }
;                 *(u32x4*)(H + ((size_t)(u.pm * (DFF / 64) + (col0 >> 6)) * 256 + (size_t)(row & 255)) * 64 + (col0 & 63)) = pack8bf(h[0], h[1]);
	v_pk_mul_f32 v[250:251], v[48:49], v[242:243] op_sel_hi:[1,0]
	v_pk_mul_f32 v[46:47], v[46:47], v[42:43]
	v_exp_f32_e32 v248, v248
	v_exp_f32_e32 v249, v249
	v_exp_f32_e32 v250, v250
	v_exp_f32_e32 v251, v251
	v_pk_mul_f32 v[48:49], v[48:49], v[44:45]
	v_pk_add_f32 v[248:249], v[248:249], 1.0 op_sel_hi:[1,0]
	v_pk_add_f32 v[250:251], v[250:251], 1.0 op_sel_hi:[1,0]
	v_rcp_f32_e32 v248, v248
	v_rcp_f32_e32 v249, v249
	v_rcp_f32_e32 v250, v250
	v_rcp_f32_e32 v251, v251
	v_pk_mul_f32 v[248:249], v[248:249], v[242:243] op_sel:[0,1] op_sel_hi:[1,1]
	v_pk_mul_f32 v[250:251], v[250:251], v[242:243] op_sel:[0,1] op_sel_hi:[1,1]
	v_pk_mul_f32 v[46:47], v[46:47], v[248:249]
	v_pk_mul_f32 v[48:49], v[48:49], v[250:251]
	v_cvt_pk_bf16_f32 v42, v46, v47
	v_cvt_pk_bf16_f32 v43, v48, v49
	v_pk_mul_f32 v[38:39], v[38:39], v[220:221]
	v_pk_mul_f32 v[40:41], v[40:41], v[222:223]
	v_pk_mul_f32 v[34:35], v[34:35], v[228:229]
	v_pk_mul_f32 v[36:37], v[36:37], v[230:231]
	v_pk_mul_f32 v[248:249], v[38:39], v[242:243] op_sel_hi:[1,0]
	v_pk_mul_f32 v[250:251], v[40:41], v[242:243] op_sel_hi:[1,0]
	v_pk_mul_f32 v[38:39], v[38:39], v[34:35]
	v_exp_f32_e32 v248, v248
	v_exp_f32_e32 v249, v249
	v_exp_f32_e32 v250, v250
	v_exp_f32_e32 v251, v251
	v_pk_mul_f32 v[40:41], v[40:41], v[36:37]
	v_pk_add_f32 v[248:249], v[248:249], 1.0 op_sel_hi:[1,0]
	v_pk_add_f32 v[250:251], v[250:251], 1.0 op_sel_hi:[1,0]
	v_rcp_f32_e32 v248, v248
	v_rcp_f32_e32 v249, v249
	v_rcp_f32_e32 v250, v250
	v_rcp_f32_e32 v251, v251
	v_pk_mul_f32 v[248:249], v[248:249], v[242:243] op_sel:[0,1] op_sel_hi:[1,1]
	v_pk_mul_f32 v[250:251], v[250:251], v[242:243] op_sel:[0,1] op_sel_hi:[1,1]
	v_pk_mul_f32 v[38:39], v[38:39], v[248:249]
	v_pk_mul_f32 v[40:41], v[40:41], v[250:251]
	v_cvt_pk_bf16_f32 v44, v38, v39
	v_cvt_pk_bf16_f32 v45, v40, v41
	global_store_dwordx4 v176, v[42:45], s[22:23] offset:2048 sc1
	v_pk_mul_f32 v[30:31], v[30:31], v[216:217]
	v_pk_mul_f32 v[32:33], v[32:33], v[218:219]
	v_pk_mul_f32 v[26:27], v[26:27], v[224:225]
	v_pk_mul_f32 v[28:29], v[28:29], v[226:227]
	v_pk_mul_f32 v[248:249], v[30:31], v[244:245] op_sel_hi:[1,0]
	v_pk_mul_f32 v[250:251], v[32:33], v[244:245] op_sel_hi:[1,0]
	v_pk_mul_f32 v[30:31], v[30:31], v[26:27]
	v_exp_f32_e32 v248, v248
	v_exp_f32_e32 v249, v249
	v_exp_f32_e32 v250, v250
	v_exp_f32_e32 v251, v251
	v_pk_mul_f32 v[32:33], v[32:33], v[28:29]
	v_pk_add_f32 v[248:249], v[248:249], 1.0 op_sel_hi:[1,0]
	v_pk_add_f32 v[250:251], v[250:251], 1.0 op_sel_hi:[1,0]
	v_rcp_f32_e32 v248, v248
	v_rcp_f32_e32 v249, v249
	v_rcp_f32_e32 v250, v250
	v_rcp_f32_e32 v251, v251
	v_pk_mul_f32 v[248:249], v[248:249], v[244:245] op_sel:[0,1] op_sel_hi:[1,1]
	v_pk_mul_f32 v[250:251], v[250:251], v[244:245] op_sel:[0,1] op_sel_hi:[1,1]
	v_pk_mul_f32 v[30:31], v[30:31], v[248:249]
	v_pk_mul_f32 v[32:33], v[32:33], v[250:251]
	v_cvt_pk_bf16_f32 v26, v30, v31
	v_cvt_pk_bf16_f32 v27, v32, v33
	v_pk_mul_f32 v[22:23], v[22:23], v[220:221]
	v_pk_mul_f32 v[24:25], v[24:25], v[222:223]
	v_pk_mul_f32 v[18:19], v[18:19], v[228:229]
	v_pk_mul_f32 v[20:21], v[20:21], v[230:231]
	v_pk_mul_f32 v[248:249], v[22:23], v[244:245] op_sel_hi:[1,0]
	v_pk_mul_f32 v[250:251], v[24:25], v[244:245] op_sel_hi:[1,0]
	v_pk_mul_f32 v[22:23], v[22:23], v[18:19]
	v_exp_f32_e32 v248, v248
	v_exp_f32_e32 v249, v249
	v_exp_f32_e32 v250, v250
	v_exp_f32_e32 v251, v251
	v_pk_mul_f32 v[24:25], v[24:25], v[20:21]
	v_pk_add_f32 v[248:249], v[248:249], 1.0 op_sel_hi:[1,0]
	v_pk_add_f32 v[250:251], v[250:251], 1.0 op_sel_hi:[1,0]
	v_rcp_f32_e32 v248, v248
	v_rcp_f32_e32 v249, v249
	v_rcp_f32_e32 v250, v250
	v_rcp_f32_e32 v251, v251
	v_pk_mul_f32 v[248:249], v[248:249], v[244:245] op_sel:[0,1] op_sel_hi:[1,1]
	v_pk_mul_f32 v[250:251], v[250:251], v[244:245] op_sel:[0,1] op_sel_hi:[1,1]
	v_pk_mul_f32 v[22:23], v[22:23], v[248:249]
	v_pk_mul_f32 v[24:25], v[24:25], v[250:251]
	v_cvt_pk_bf16_f32 v28, v22, v23
	v_cvt_pk_bf16_f32 v29, v24, v25
	s_add_u32 s22, s20, 0x5000
	s_addc_u32 s23, s21, 0
	global_store_dwordx4 v176, v[26:29], s[22:23] sc1
	v_pk_mul_f32 v[14:15], v[14:15], v[216:217]
	v_pk_mul_f32 v[16:17], v[16:17], v[218:219]
	v_pk_mul_f32 v[10:11], v[10:11], v[224:225]
	v_pk_mul_f32 v[12:13], v[12:13], v[226:227]
	v_pk_mul_f32 v[248:249], v[14:15], v[246:247] op_sel_hi:[1,0]
	v_pk_mul_f32 v[250:251], v[16:17], v[246:247] op_sel_hi:[1,0]
	v_pk_mul_f32 v[14:15], v[14:15], v[10:11]
	v_exp_f32_e32 v248, v248
	v_exp_f32_e32 v249, v249
	v_exp_f32_e32 v250, v250
	v_exp_f32_e32 v251, v251
	v_pk_mul_f32 v[16:17], v[16:17], v[12:13]
	v_pk_add_f32 v[248:249], v[248:249], 1.0 op_sel_hi:[1,0]
	v_pk_add_f32 v[250:251], v[250:251], 1.0 op_sel_hi:[1,0]
	v_rcp_f32_e32 v248, v248
	v_rcp_f32_e32 v249, v249
	v_rcp_f32_e32 v250, v250
	v_rcp_f32_e32 v251, v251
	v_pk_mul_f32 v[248:249], v[248:249], v[246:247] op_sel:[0,1] op_sel_hi:[1,1]
	v_pk_mul_f32 v[250:251], v[250:251], v[246:247] op_sel:[0,1] op_sel_hi:[1,1]
	v_pk_mul_f32 v[14:15], v[14:15], v[248:249]
	v_pk_mul_f32 v[16:17], v[16:17], v[250:251]
	v_cvt_pk_bf16_f32 v10, v14, v15
	v_cvt_pk_bf16_f32 v11, v16, v17
	v_pk_mul_f32 v[6:7], v[6:7], v[220:221]
	v_pk_mul_f32 v[8:9], v[8:9], v[222:223]
	v_pk_mul_f32 v[2:3], v[2:3], v[228:229]
	v_pk_mul_f32 v[4:5], v[4:5], v[230:231]
	v_pk_mul_f32 v[248:249], v[6:7], v[246:247] op_sel_hi:[1,0]
	v_pk_mul_f32 v[250:251], v[8:9], v[246:247] op_sel_hi:[1,0]
	v_pk_mul_f32 v[6:7], v[6:7], v[2:3]
	v_exp_f32_e32 v248, v248
	v_exp_f32_e32 v249, v249
	v_exp_f32_e32 v250, v250
	v_exp_f32_e32 v251, v251
	v_pk_mul_f32 v[8:9], v[8:9], v[4:5]
	v_pk_add_f32 v[248:249], v[248:249], 1.0 op_sel_hi:[1,0]
	v_pk_add_f32 v[250:251], v[250:251], 1.0 op_sel_hi:[1,0]
	v_rcp_f32_e32 v248, v248
	v_rcp_f32_e32 v249, v249
	v_rcp_f32_e32 v250, v250
	v_rcp_f32_e32 v251, v251
	v_pk_mul_f32 v[248:249], v[248:249], v[246:247] op_sel:[0,1] op_sel_hi:[1,1]
	v_pk_mul_f32 v[250:251], v[250:251], v[246:247] op_sel:[0,1] op_sel_hi:[1,1]
	v_pk_mul_f32 v[6:7], v[6:7], v[248:249]
	v_pk_mul_f32 v[8:9], v[8:9], v[250:251]
	v_cvt_pk_bf16_f32 v12, v6, v7
	v_cvt_pk_bf16_f32 v13, v8, v9
	global_store_dwordx4 v176, v[10:13], s[22:23] offset:2048 sc1
	s_mov_b64 s[20:21], -1
	s_andn2_b64 vcc, exec, s[4:5]
	s_cbranch_vccnz .LBB0_159
	s_andn2_b64 vcc, exec, s[6:7]
	s_cbranch_vccnz .LBB0_158
	s_barrier
	s_branch .LBB0_158
